# GEMM K-loop: each run of 8 independent MFMAs reordered into a snake (consecutive MFMAs share an operand) to cut operand switching on the matrix pipe; on top of opt2
# speedup vs baseline: 1.0055x; 1.0055x over previous
; #define PG8_STAGE(bufoff, gbase, voff) do { _Pragma("unroll") for (int _i = 0; _i < 2; ++_i) \
;         __builtin_amdgcn_global_load_lds((const unsigned*)((const char*)(gbase) + (voff)[_i]), (PG8_LAS unsigned*)(lds + (bufoff) + ldsw + _i * 8192), 16, 0, 0); } while (0)
; #define PG8_LDA(dst, b, h) do { _Pragma("unroll") for (int m = 0; m < 4; ++m) _Pragma("unroll") for (int k = 0; k < 2; ++k) dst[m][k] = *(const PG8_LAS bf16x8*)(lds + PG8_SA(b, h) + aoff + m * 2048 + k * 1024); } while (0)
; #define PG8_LDB(dst, b, h) do { _Pragma("unroll") for (int n = 0; n < 2; ++n) _Pragma("unroll") for (int k = 0; k < 2; ++k) dst[n][k] = *(const PG8_LAS bf16x8*)(lds + PG8_SB(b, h) + boff + n * 2048 + k * 1024); } while (0)
; #define PG8_BAR __builtin_amdgcn_s_barrier()
; template <class Epi, class Sched, bool ALIGN_EPI = false, bool SP2 = false>
; __device__ __forceinline__ void gemm_phase(PG8_LAS unsigned char* lds, const Gemm g, const Sched& S, const Epi& E) {
;     ...
;             const bool last = (t == nt - 2);
;             const char* a1 = cA + (size_t)(t + 1) * kstep;
;             const char* a2 = last ? nA : cA + (size_t)(t + 2) * kstep; const char* b2 = last ? nB : cB + (size_t)(t + 2) * kstep;
;             const char* a3 = a2 + kstep; const char* b3 = b2 + kstep;
;             if (last && has_next) S.a_ready(nxt);
;             if constexpr (SP2) {
;             PG8_LDB(B0, 0, 0); PG8_LDB(B1, 0, 1); PG8_SCHED; PG8_LDA(At, 0, 0); PG8_STAGE(PG8_SA(1, 1), a1 + hstep, voffA);
;             PG8_WAIT_V(8); PG8_WAIT_L(0); PG8_BAR; PG8_MMA(0, 0, At, B0); PG8_MMA(0, 1, At, B1); PG8_BAR; PG8_SCHED;
;             PG8_LDA(At, 0, 1); PG8_STAGE(PG8_SB(0, 0), b2, voffB); PG8_STAGE(PG8_SB(0, 1), b2 + hstep, voffB); PG8_STAGE(PG8_SA(0, 0), a2, voffA);
;             PG8_WAIT_V(8); PG8_WAIT_L(0); PG8_BAR; PG8_MMA(1, 0, At, B0); PG8_MMA(1, 1, At, B1); PG8_BAR; PG8_SCHED;
;             PG8_LDB(B0, 1, 0); PG8_LDB(B1, 1, 1); PG8_SCHED; PG8_LDA(At, 1, 0); PG8_STAGE(PG8_SA(0, 1), a2 + hstep, voffA);
;             PG8_WAIT_V(8); PG8_WAIT_L(0); PG8_BAR; PG8_MMA(0, 0, At, B0); PG8_MMA(0, 1, At, B1); PG8_BAR; PG8_SCHED;
;             PG8_LDA(At, 1, 1); PG8_STAGE(PG8_SB(1, 0), b3, voffB); PG8_STAGE(PG8_SB(1, 1), b3 + hstep, voffB); PG8_STAGE(PG8_SA(1, 0), a3, voffA);
;             PG8_WAIT_V(8); PG8_WAIT_L(0); PG8_BAR; PG8_MMA(1, 0, At, B0); PG8_MMA(1, 1, At, B1); PG8_BAR; PG8_SCHED;
.LBB0_56:
	s_add_i32 s2, s34, 2
	s_add_u32 s35, s28, s30
	s_addc_u32 s62, s29, s31
	s_add_u32 s63, s35, 0x100
	s_addc_u32 s35, s62, 0
	s_add_u32 s62, s60, s30
	s_addc_u32 s64, s61, s31
	s_add_i32 s65, 0, 0x10000
	s_cmp_eq_u32 s48, s34
	s_cselect_b32 s35, s1, s35
	s_cselect_b32 s34, s0, s63
	v_add_u32_e32 v0, s65, v188
	s_cselect_b32 s63, s27, s64
	s_cselect_b32 s62, s26, s62
	s_add_i32 s64, 0, 0x14000
	ds_read_b128 v[132:135], v0
	ds_read_b128 v[136:139], v0 offset:1024
	ds_read_b128 v[140:143], v0 offset:2048
	ds_read_b128 v[144:147], v0 offset:3072
	v_add_u32_e32 v0, s64, v188
	ds_read_b128 v[148:151], v0
	ds_read_b128 v[152:155], v0 offset:1024
	ds_read_b128 v[156:159], v0 offset:2048
	ds_read_b128 v[160:163], v0 offset:3072
	v_lshl_add_u64 v[2:3], v[204:205], 0, s[30:31]
	s_add_i32 m0, s43, 0xc000
	ds_read_b128 v[164:167], v235
	ds_read_b128 v[168:171], v235 offset:1024
	ds_read_b128 v[172:175], v235 offset:2048
	ds_read_b128 v[176:179], v235 offset:3072
	ds_read_b128 v[180:183], v235 offset:4096
	ds_read_b128 v[184:187], v235 offset:5120
	ds_read_b128 v[236:239], v235 offset:6144
	ds_read_b128 v[240:243], v235 offset:7168
	global_load_lds_dwordx4 v[2:3], off
	v_lshl_add_u64 v[2:3], v[206:207], 0, s[30:31]
	s_add_i32 m0, s43, 0xe000
	s_nop 0
	global_load_lds_dwordx4 v[2:3], off
	s_waitcnt vmcnt(8)
	s_waitcnt lgkmcnt(0)
	s_barrier
	s_setprio 1
	s_waitcnt lgkmcnt(0)
	v_mfma_f32_16x16x32_bf16 v[116:119], v[132:135], v[164:167], v[116:119]
	v_mfma_f32_16x16x32_bf16 v[120:123], v[140:143], v[164:167], v[120:123]
	v_mfma_f32_16x16x32_bf16 v[104:107], v[140:143], v[172:175], v[104:107]
	v_mfma_f32_16x16x32_bf16 v[100:103], v[132:135], v[172:175], v[100:103]
	v_mfma_f32_16x16x32_bf16 v[76:79], v[132:135], v[180:183], v[76:79]
	v_mfma_f32_16x16x32_bf16 v[80:83], v[140:143], v[180:183], v[80:83]
	v_mfma_f32_16x16x32_bf16 v[48:51], v[140:143], v[236:239], v[48:51]
	v_mfma_f32_16x16x32_bf16 v[44:47], v[132:135], v[236:239], v[44:47]
	v_mfma_f32_16x16x32_bf16 v[116:119], v[136:139], v[168:171], v[116:119]
	v_mfma_f32_16x16x32_bf16 v[120:123], v[144:147], v[168:171], v[120:123]
	v_mfma_f32_16x16x32_bf16 v[104:107], v[144:147], v[176:179], v[104:107]
	v_mfma_f32_16x16x32_bf16 v[100:103], v[136:139], v[176:179], v[100:103]
	v_mfma_f32_16x16x32_bf16 v[76:79], v[136:139], v[184:187], v[76:79]
	v_mfma_f32_16x16x32_bf16 v[80:83], v[144:147], v[184:187], v[80:83]
	v_mfma_f32_16x16x32_bf16 v[48:51], v[144:147], v[240:243], v[48:51]
	v_mfma_f32_16x16x32_bf16 v[44:47], v[136:139], v[240:243], v[44:47]
	s_setprio 0
	s_setprio 1
	v_mfma_f32_16x16x32_bf16 v[124:127], v[148:151], v[164:167], v[124:127]
	v_mfma_f32_16x16x32_bf16 v[128:131], v[156:159], v[164:167], v[128:131]
	v_mfma_f32_16x16x32_bf16 v[112:115], v[156:159], v[172:175], v[112:115]
	v_mfma_f32_16x16x32_bf16 v[108:111], v[148:151], v[172:175], v[108:111]
	v_mfma_f32_16x16x32_bf16 v[92:95], v[148:151], v[180:183], v[92:95]
	v_mfma_f32_16x16x32_bf16 v[96:99], v[156:159], v[180:183], v[96:99]
	v_mfma_f32_16x16x32_bf16 v[72:75], v[156:159], v[236:239], v[72:75]
	v_mfma_f32_16x16x32_bf16 v[68:71], v[148:151], v[236:239], v[68:71]
	v_mfma_f32_16x16x32_bf16 v[124:127], v[152:155], v[168:171], v[124:127]
	v_mfma_f32_16x16x32_bf16 v[128:131], v[160:163], v[168:171], v[128:131]
	v_mfma_f32_16x16x32_bf16 v[112:115], v[160:163], v[176:179], v[112:115]
	v_mfma_f32_16x16x32_bf16 v[108:111], v[152:155], v[176:179], v[108:111]
	v_mfma_f32_16x16x32_bf16 v[92:95], v[152:155], v[184:187], v[92:95]
	v_mfma_f32_16x16x32_bf16 v[96:99], v[160:163], v[184:187], v[96:99]
	v_mfma_f32_16x16x32_bf16 v[72:75], v[160:163], v[240:243], v[72:75]
	v_mfma_f32_16x16x32_bf16 v[68:71], v[152:155], v[240:243], v[68:71]
	s_setprio 0
	s_barrier
	s_add_i32 s65, s65, s41
	v_lshl_add_u64 v[208:209], s[62:63], 0, v[192:193]
	s_mov_b32 m0, s65
	ds_read_b128 v[164:167], v235 offset:16384
	ds_read_b128 v[168:171], v235 offset:17408
	ds_read_b128 v[172:175], v235 offset:18432
	ds_read_b128 v[176:179], v235 offset:19456
	ds_read_b128 v[180:183], v235 offset:20480
	ds_read_b128 v[184:187], v235 offset:21504
	ds_read_b128 v[236:239], v235 offset:22528
	ds_read_b128 v[240:243], v235 offset:23552
	global_load_lds_dwordx4 v[208:209], off
	s_add_i32 m0, s65, 0x2000
	v_lshl_add_u64 v[244:245], s[62:63], 0, v[196:197]
	s_add_u32 s62, s62, s16
	s_addc_u32 s63, s63, 0
	s_add_i32 s64, s64, s41
	global_load_lds_dwordx4 v[244:245], off
	v_lshl_add_u64 v[246:247], s[62:63], 0, v[192:193]
	s_mov_b32 m0, s64
	v_lshl_add_u64 v[248:249], s[62:63], 0, v[196:197]
	global_load_lds_dwordx4 v[246:247], off
	s_add_i32 m0, s64, 0x2000
	v_lshl_add_u64 v[250:251], s[34:35], 0, v[190:191]
	global_load_lds_dwordx4 v[248:249], off
	s_mov_b32 m0, s43
	v_lshl_add_u64 v[212:213], s[34:35], 0, v[194:195]
	global_load_lds_dwordx4 v[250:251], off
	s_mov_b32 m0, s44
	s_nop 0
	global_load_lds_dwordx4 v[212:213], off
	s_waitcnt vmcnt(8)
	s_waitcnt lgkmcnt(0)
	s_barrier
; #define PG8_STAGE(bufoff, gbase, voff) do { _Pragma("unroll") for (int _i = 0; _i < 2; ++_i) \
;         __builtin_amdgcn_global_load_lds((const unsigned*)((const char*)(gbase) + (voff)[_i]), (PG8_LAS unsigned*)(lds + (bufoff) + ldsw + _i * 8192), 16, 0, 0); } while (0)
; #define PG8_LDA(dst, b, h) do { _Pragma("unroll") for (int m = 0; m < 4; ++m) _Pragma("unroll") for (int k = 0; k < 2; ++k) dst[m][k] = *(const PG8_LAS bf16x8*)(lds + PG8_SA(b, h) + aoff + m * 2048 + k * 1024); } while (0)
; #define PG8_LDB(dst, b, h) do { _Pragma("unroll") for (int n = 0; n < 2; ++n) _Pragma("unroll") for (int k = 0; k < 2; ++k) dst[n][k] = *(const PG8_LAS bf16x8*)(lds + PG8_SB(b, h) + boff + n * 2048 + k * 1024); } while (0)
; #define PG8_MMA(ai, bj, At, Bt) do { __builtin_amdgcn_s_setprio(1); _Pragma("unroll") for (int m = 0; m < 4; ++m) _Pragma("unroll") for (int n = 0; n < 2; ++n) _Pragma("unroll") for (int k = 0; k < 2; ++k) \
;         acc[ai][bj][m][n] = __builtin_amdgcn_mfma_f32_16x16x32_bf16(Bt[n][k], At[m][k], acc[ai][bj][m][n], 0, 0, 0); __builtin_amdgcn_s_setprio(0); } while (0)
; #define PG8_WAIT_V(n) asm volatile("s_waitcnt vmcnt(" #n ")" ::: "memory")
; template <class Epi, class Sched, bool ALIGN_EPI = false, bool SP2 = false>
; __device__ __forceinline__ void gemm_phase(PG8_LAS unsigned char* lds, const Gemm g, const Sched& S, const Epi& E) {
;     ...
;             PG8_LDB(B0, 0, 0); PG8_LDB(B1, 0, 1); PG8_SCHED; PG8_LDA(At, 0, 0); PG8_STAGE(PG8_SA(1, 1), a1 + hstep, voffA);
;             PG8_WAIT_V(8); PG8_WAIT_L(0); PG8_BAR; PG8_MMA(0, 0, At, B0); PG8_MMA(0, 1, At, B1); PG8_BAR; PG8_SCHED;
;             PG8_LDA(At, 0, 1); PG8_STAGE(PG8_SB(0, 0), b2, voffB); PG8_STAGE(PG8_SB(0, 1), b2 + hstep, voffB); PG8_STAGE(PG8_SA(0, 0), a2, voffA);
;             PG8_WAIT_V(8); PG8_WAIT_L(0); PG8_BAR; PG8_MMA(1, 0, At, B0); PG8_MMA(1, 1, At, B1); PG8_BAR; PG8_SCHED;
;             PG8_LDB(B0, 1, 0); PG8_LDB(B1, 1, 1); PG8_SCHED; PG8_LDA(At, 1, 0); PG8_STAGE(PG8_SA(0, 1), a2 + hstep, voffA);
;             PG8_WAIT_V(8); PG8_WAIT_L(0); PG8_BAR; PG8_MMA(0, 0, At, B0); PG8_MMA(0, 1, At, B1); PG8_BAR; PG8_SCHED;
;             PG8_LDA(At, 1, 1); PG8_STAGE(PG8_SB(1, 0), b3, voffB); PG8_STAGE(PG8_SB(1, 1), b3 + hstep, voffB); PG8_STAGE(PG8_SA(1, 0), a3, voffA);
;             PG8_WAIT_V(8); PG8_WAIT_L(0); PG8_BAR; PG8_MMA(1, 0, At, B0); PG8_MMA(1, 1, At, B1); PG8_BAR; PG8_SCHED;
	s_setprio 1
	s_waitcnt lgkmcnt(0)
	v_mfma_f32_16x16x32_bf16 v[60:63], v[132:135], v[164:167], v[60:63]
	v_mfma_f32_16x16x32_bf16 v[64:67], v[140:143], v[164:167], v[64:67]
	v_mfma_f32_16x16x32_bf16 v[40:43], v[140:143], v[172:175], v[40:43]
	v_mfma_f32_16x16x32_bf16 v[36:39], v[132:135], v[172:175], v[36:39]
	v_mfma_f32_16x16x32_bf16 v[20:23], v[132:135], v[180:183], v[20:23]
	v_mfma_f32_16x16x32_bf16 v[24:27], v[140:143], v[180:183], v[24:27]
	v_mfma_f32_16x16x32_bf16 v[2:5], v[132:135], v[236:239], v[4:7]
	v_mfma_f32_16x16x32_bf16 v[6:9], v[140:143], v[236:239], v[8:11]
	v_mfma_f32_16x16x32_bf16 v[60:63], v[136:139], v[168:171], v[60:63]
	v_mfma_f32_16x16x32_bf16 v[64:67], v[144:147], v[168:171], v[64:67]
	v_mfma_f32_16x16x32_bf16 v[40:43], v[144:147], v[176:179], v[40:43]
	v_mfma_f32_16x16x32_bf16 v[36:39], v[136:139], v[176:179], v[36:39]
	v_mfma_f32_16x16x32_bf16 v[20:23], v[136:139], v[184:187], v[20:23]
	v_mfma_f32_16x16x32_bf16 v[24:27], v[144:147], v[184:187], v[24:27]
	v_mfma_f32_16x16x32_bf16 v[2:5], v[136:139], v[240:243], v[2:5]
	v_mfma_f32_16x16x32_bf16 v[8:11], v[144:147], v[240:243], v[6:9]
	s_setprio 0
	s_setprio 1
	v_mfma_f32_16x16x32_bf16 v[84:87], v[148:151], v[164:167], v[84:87]
	v_mfma_f32_16x16x32_bf16 v[88:91], v[156:159], v[164:167], v[88:91]
	v_mfma_f32_16x16x32_bf16 v[56:59], v[156:159], v[172:175], v[56:59]
	v_mfma_f32_16x16x32_bf16 v[52:55], v[148:151], v[172:175], v[52:55]
	v_mfma_f32_16x16x32_bf16 v[28:31], v[148:151], v[180:183], v[28:31]
	v_mfma_f32_16x16x32_bf16 v[32:35], v[156:159], v[180:183], v[32:35]
	v_mfma_f32_16x16x32_bf16 v[16:19], v[156:159], v[236:239], v[16:19]
	v_mfma_f32_16x16x32_bf16 v[12:15], v[148:151], v[236:239], v[12:15]
	v_mfma_f32_16x16x32_bf16 v[84:87], v[152:155], v[168:171], v[84:87]
	v_mfma_f32_16x16x32_bf16 v[88:91], v[160:163], v[168:171], v[88:91]
	v_mfma_f32_16x16x32_bf16 v[56:59], v[160:163], v[176:179], v[56:59]
	v_mfma_f32_16x16x32_bf16 v[52:55], v[152:155], v[176:179], v[52:55]
	v_mfma_f32_16x16x32_bf16 v[28:31], v[152:155], v[184:187], v[28:31]
	v_mfma_f32_16x16x32_bf16 v[32:35], v[160:163], v[184:187], v[32:35]
	v_mfma_f32_16x16x32_bf16 v[16:19], v[160:163], v[240:243], v[16:19]
	v_mfma_f32_16x16x32_bf16 v[12:15], v[152:155], v[240:243], v[12:15]
	s_setprio 0
	s_barrier
	s_add_i32 s62, 0, 0x18000
	v_add_u32_e32 v0, s62, v188
	s_add_i32 s63, 0, 0x1c000
	ds_read_b128 v[132:135], v0
	ds_read_b128 v[136:139], v0 offset:1024
	ds_read_b128 v[140:143], v0 offset:2048
	ds_read_b128 v[144:147], v0 offset:3072
	v_add_u32_e32 v0, s63, v188
	ds_read_b128 v[148:151], v0
	ds_read_b128 v[152:155], v0 offset:1024
	ds_read_b128 v[156:159], v0 offset:2048
	ds_read_b128 v[160:163], v0 offset:3072
	s_add_u32 s34, s34, s16
	s_addc_u32 s35, s35, 0
	s_mov_b32 m0, s45
	v_lshl_add_u64 v[6:7], s[34:35], 0, v[190:191]
	ds_read_b128 v[164:167], v235 offset:32768
	ds_read_b128 v[168:171], v235 offset:33792
	ds_read_b128 v[172:175], v235 offset:34816
	ds_read_b128 v[176:179], v235 offset:35840
	ds_read_b128 v[180:183], v235 offset:36864
	ds_read_b128 v[184:187], v235 offset:37888
	ds_read_b128 v[236:239], v235 offset:38912
	ds_read_b128 v[240:243], v235 offset:39936
	global_load_lds_dwordx4 v[6:7], off
	v_lshl_add_u64 v[6:7], s[34:35], 0, v[194:195]
	s_mov_b32 m0, s46
	s_nop 0
	global_load_lds_dwordx4 v[6:7], off
	s_waitcnt vmcnt(8)
	s_waitcnt lgkmcnt(0)
	s_barrier
	s_setprio 1
	s_waitcnt lgkmcnt(0)
	v_mfma_f32_16x16x32_bf16 v[116:119], v[132:135], v[164:167], v[116:119]
	v_mfma_f32_16x16x32_bf16 v[120:123], v[140:143], v[164:167], v[120:123]
	v_mfma_f32_16x16x32_bf16 v[104:107], v[140:143], v[172:175], v[104:107]
	v_mfma_f32_16x16x32_bf16 v[100:103], v[132:135], v[172:175], v[100:103]
	v_mfma_f32_16x16x32_bf16 v[76:79], v[132:135], v[180:183], v[76:79]
	v_mfma_f32_16x16x32_bf16 v[80:83], v[140:143], v[180:183], v[80:83]
	v_mfma_f32_16x16x32_bf16 v[48:51], v[140:143], v[236:239], v[48:51]
	v_mfma_f32_16x16x32_bf16 v[44:47], v[132:135], v[236:239], v[44:47]
	v_mfma_f32_16x16x32_bf16 v[116:119], v[136:139], v[168:171], v[116:119]
	v_mfma_f32_16x16x32_bf16 v[120:123], v[144:147], v[168:171], v[120:123]
	v_mfma_f32_16x16x32_bf16 v[104:107], v[144:147], v[176:179], v[104:107]
	v_mfma_f32_16x16x32_bf16 v[100:103], v[136:139], v[176:179], v[100:103]
	v_mfma_f32_16x16x32_bf16 v[76:79], v[136:139], v[184:187], v[76:79]
	v_mfma_f32_16x16x32_bf16 v[80:83], v[144:147], v[184:187], v[80:83]
	v_mfma_f32_16x16x32_bf16 v[48:51], v[144:147], v[240:243], v[48:51]
	v_mfma_f32_16x16x32_bf16 v[44:47], v[136:139], v[240:243], v[44:47]
	s_setprio 0
	s_setprio 1
	v_mfma_f32_16x16x32_bf16 v[124:127], v[148:151], v[164:167], v[124:127]
	v_mfma_f32_16x16x32_bf16 v[128:131], v[156:159], v[164:167], v[128:131]
	v_mfma_f32_16x16x32_bf16 v[112:115], v[156:159], v[172:175], v[112:115]
	v_mfma_f32_16x16x32_bf16 v[108:111], v[148:151], v[172:175], v[108:111]
	v_mfma_f32_16x16x32_bf16 v[92:95], v[148:151], v[180:183], v[92:95]
	v_mfma_f32_16x16x32_bf16 v[96:99], v[156:159], v[180:183], v[96:99]
	v_mfma_f32_16x16x32_bf16 v[72:75], v[156:159], v[236:239], v[72:75]
	v_mfma_f32_16x16x32_bf16 v[68:71], v[148:151], v[236:239], v[68:71]
	v_mfma_f32_16x16x32_bf16 v[124:127], v[152:155], v[168:171], v[124:127]
	v_mfma_f32_16x16x32_bf16 v[128:131], v[160:163], v[168:171], v[128:131]
	v_mfma_f32_16x16x32_bf16 v[112:115], v[160:163], v[176:179], v[112:115]
	v_mfma_f32_16x16x32_bf16 v[108:111], v[152:155], v[176:179], v[108:111]
	v_mfma_f32_16x16x32_bf16 v[92:95], v[152:155], v[184:187], v[92:95]
	v_mfma_f32_16x16x32_bf16 v[96:99], v[160:163], v[184:187], v[96:99]
	v_mfma_f32_16x16x32_bf16 v[72:75], v[160:163], v[240:243], v[72:75]
	v_mfma_f32_16x16x32_bf16 v[68:71], v[152:155], v[240:243], v[68:71]
	s_setprio 0
	s_barrier
; #define PG8_STAGE(bufoff, gbase, voff) do { _Pragma("unroll") for (int _i = 0; _i < 2; ++_i) \
;         __builtin_amdgcn_global_load_lds((const unsigned*)((const char*)(gbase) + (voff)[_i]), (PG8_LAS unsigned*)(lds + (bufoff) + ldsw + _i * 8192), 16, 0, 0); } while (0)
; #define PG8_LDA(dst, b, h) do { _Pragma("unroll") for (int m = 0; m < 4; ++m) _Pragma("unroll") for (int k = 0; k < 2; ++k) dst[m][k] = *(const PG8_LAS bf16x8*)(lds + PG8_SA(b, h) + aoff + m * 2048 + k * 1024); } while (0)
; #define PG8_LDB(dst, b, h) do { _Pragma("unroll") for (int n = 0; n < 2; ++n) _Pragma("unroll") for (int k = 0; k < 2; ++k) dst[n][k] = *(const PG8_LAS bf16x8*)(lds + PG8_SB(b, h) + boff + n * 2048 + k * 1024); } while (0)
; #define PG8_MMA(ai, bj, At, Bt) do { __builtin_amdgcn_s_setprio(1); _Pragma("unroll") for (int m = 0; m < 4; ++m) _Pragma("unroll") for (int n = 0; n < 2; ++n) _Pragma("unroll") for (int k = 0; k < 2; ++k) \
;         acc[ai][bj][m][n] = __builtin_amdgcn_mfma_f32_16x16x32_bf16(Bt[n][k], At[m][k], acc[ai][bj][m][n], 0, 0, 0); __builtin_amdgcn_s_setprio(0); } while (0)
; #define PG8_WAIT_V(n) asm volatile("s_waitcnt vmcnt(" #n ")" ::: "memory")
; #define PG8_WAIT_L(n) asm volatile("s_waitcnt lgkmcnt(" #n ")" ::: "memory")
; #define PG8_BAR __builtin_amdgcn_s_barrier()
; #define PG8_SCHED __builtin_amdgcn_sched_barrier(0)
; template <class Epi, class Sched, bool ALIGN_EPI = false, bool SP2 = false>
; __device__ __forceinline__ void gemm_phase(PG8_LAS unsigned char* lds, const Gemm g, const Sched& S, const Epi& E) {
;     ...
;             PG8_LDB(B0, 1, 0); PG8_LDB(B1, 1, 1); PG8_SCHED; PG8_LDA(At, 1, 0); PG8_STAGE(PG8_SA(0, 1), a2 + hstep, voffA);
;             PG8_WAIT_V(8); PG8_WAIT_L(0); PG8_BAR; PG8_MMA(0, 0, At, B0); PG8_MMA(0, 1, At, B1); PG8_BAR; PG8_SCHED;
;             PG8_LDA(At, 1, 1); PG8_STAGE(PG8_SB(1, 0), b3, voffB); PG8_STAGE(PG8_SB(1, 1), b3 + hstep, voffB); PG8_STAGE(PG8_SA(1, 0), a3, voffA);
;             PG8_WAIT_V(8); PG8_WAIT_L(0); PG8_BAR; PG8_MMA(1, 0, At, B0); PG8_MMA(1, 1, At, B1); PG8_BAR; PG8_SCHED;
	s_add_i32 s34, s62, s41
	v_lshl_add_u64 v[6:7], v[208:209], 0, s[92:93]
	s_mov_b32 m0, s34
	ds_read_b128 v[164:167], v235 offset:49152
	ds_read_b128 v[168:171], v235 offset:50176
	ds_read_b128 v[172:175], v235 offset:51200
	ds_read_b128 v[176:179], v235 offset:52224
	ds_read_b128 v[180:183], v235 offset:53248
	ds_read_b128 v[184:187], v235 offset:54272
	ds_read_b128 v[236:239], v235 offset:55296
	ds_read_b128 v[240:243], v235 offset:56320
	global_load_lds_dwordx4 v[6:7], off
	v_lshl_add_u64 v[6:7], v[244:245], 0, s[92:93]
	s_add_i32 m0, s34, 0x2000
	s_add_i32 s34, s63, s41
	global_load_lds_dwordx4 v[6:7], off
	v_lshl_add_u64 v[6:7], v[246:247], 0, s[92:93]
	s_mov_b32 m0, s34
	s_nop 0
	global_load_lds_dwordx4 v[6:7], off
	v_lshl_add_u64 v[6:7], v[248:249], 0, s[92:93]
	s_add_i32 m0, s34, 0x2000
	s_nop 0
	global_load_lds_dwordx4 v[6:7], off
	v_lshl_add_u64 v[6:7], v[250:251], 0, s[92:93]
	s_mov_b32 m0, s51
	s_nop 0
	global_load_lds_dwordx4 v[6:7], off
	v_lshl_add_u64 v[6:7], v[212:213], 0, s[92:93]
	s_mov_b32 m0, s52
	s_nop 0
	global_load_lds_dwordx4 v[6:7], off
	s_waitcnt vmcnt(8)
	s_waitcnt lgkmcnt(0)
	s_barrier
	s_setprio 1
	s_waitcnt lgkmcnt(0)
	v_mfma_f32_16x16x32_bf16 v[60:63], v[132:135], v[164:167], v[60:63]
	v_mfma_f32_16x16x32_bf16 v[64:67], v[140:143], v[164:167], v[64:67]
	v_mfma_f32_16x16x32_bf16 v[40:43], v[140:143], v[172:175], v[40:43]
	v_mfma_f32_16x16x32_bf16 v[36:39], v[132:135], v[172:175], v[36:39]
	v_mfma_f32_16x16x32_bf16 v[20:23], v[132:135], v[180:183], v[20:23]
	v_mfma_f32_16x16x32_bf16 v[24:27], v[140:143], v[180:183], v[24:27]
	v_mfma_f32_16x16x32_bf16 v[8:11], v[140:143], v[236:239], v[8:11]
	v_mfma_f32_16x16x32_bf16 v[2:5], v[132:135], v[236:239], v[2:5]
	v_mfma_f32_16x16x32_bf16 v[60:63], v[136:139], v[168:171], v[60:63]
	v_mfma_f32_16x16x32_bf16 v[64:67], v[144:147], v[168:171], v[64:67]
	v_mfma_f32_16x16x32_bf16 v[40:43], v[144:147], v[176:179], v[40:43]
	v_mfma_f32_16x16x32_bf16 v[36:39], v[136:139], v[176:179], v[36:39]
	v_mfma_f32_16x16x32_bf16 v[20:23], v[136:139], v[184:187], v[20:23]
	v_mfma_f32_16x16x32_bf16 v[24:27], v[144:147], v[184:187], v[24:27]
	v_mfma_f32_16x16x32_bf16 v[4:7], v[136:139], v[240:243], v[2:5]
	v_mfma_f32_16x16x32_bf16 v[8:11], v[144:147], v[240:243], v[8:11]
	s_setprio 0
	s_setprio 1
	v_mfma_f32_16x16x32_bf16 v[84:87], v[148:151], v[164:167], v[84:87]
	v_mfma_f32_16x16x32_bf16 v[88:91], v[156:159], v[164:167], v[88:91]
	v_mfma_f32_16x16x32_bf16 v[56:59], v[156:159], v[172:175], v[56:59]
	v_mfma_f32_16x16x32_bf16 v[52:55], v[148:151], v[172:175], v[52:55]
	v_mfma_f32_16x16x32_bf16 v[28:31], v[148:151], v[180:183], v[28:31]
	v_mfma_f32_16x16x32_bf16 v[32:35], v[156:159], v[180:183], v[32:35]
	v_mfma_f32_16x16x32_bf16 v[16:19], v[156:159], v[236:239], v[16:19]
	v_mfma_f32_16x16x32_bf16 v[12:15], v[148:151], v[236:239], v[12:15]
	v_mfma_f32_16x16x32_bf16 v[84:87], v[152:155], v[168:171], v[84:87]
	v_mfma_f32_16x16x32_bf16 v[88:91], v[160:163], v[168:171], v[88:91]
	v_mfma_f32_16x16x32_bf16 v[56:59], v[160:163], v[176:179], v[56:59]
	v_mfma_f32_16x16x32_bf16 v[52:55], v[152:155], v[176:179], v[52:55]
	v_mfma_f32_16x16x32_bf16 v[28:31], v[152:155], v[184:187], v[28:31]
	v_mfma_f32_16x16x32_bf16 v[32:35], v[160:163], v[184:187], v[32:35]
	v_mfma_f32_16x16x32_bf16 v[16:19], v[160:163], v[240:243], v[16:19]
	v_mfma_f32_16x16x32_bf16 v[12:15], v[152:155], v[240:243], v[12:15]
	s_setprio 0
	s_barrier
	s_add_u32 s30, s30, 0x100
	s_addc_u32 s31, s31, 0
	s_cmp_ge_u32 s2, s47
	s_cbranch_scc1 .LBB0_58
	s_mov_b32 s34, s2
	s_branch .LBB0_54
